# combo14: combo11 + GEMM phase prologues issue the K-tile 1 stage loads together with K-tile 0's (first wait moved after them, vmcnt(2)->vmcnt(8))
# speedup vs baseline: 1.0062x; 1.0047x over previous
; __device__ __forceinline__ int opaque_tid() { int t = threadIdx.x; asm volatile("" : "+v"(t)); return t; }
; #define PG8_STAGE(bufoff, gbase, voff) do { _Pragma("unroll") for (int _i = 0; _i < 2; ++_i) \
;         __builtin_amdgcn_global_load_lds((const unsigned*)((const char*)(gbase) + (voff)[_i]), (PG8_LAS unsigned*)(lds + (bufoff) + ldsw + _i * 8192), 16, 0, 0); } while (0)
; #define PG8_WAIT_V(n) asm volatile("s_waitcnt vmcnt(" #n ")" ::: "memory")
; #define PG8_BAR __builtin_amdgcn_s_barrier()
; template <class Epi, class Sched, bool ALIGN_EPI = false, bool SP2 = false>
; __device__ __forceinline__ void gemm_phase(PG8_LAS unsigned char* lds, const Gemm g, const Sched& S, const Epi& E) {
;     const int tid = opaque_tid(), wid = __builtin_amdgcn_readfirstlane(tid >> 6), lane = tid & 63, wr = wid >> 2, wc = wid & 3, fr = lane & 15, fq = lane >> 4;
;     const int K = g.K, nt = K / BK;
;     unsigned voffA[2], voffB[2];
; #pragma unroll
;     for (int i = 0; i < 2; ++i) { int R, C; stage_rc(tid * 16 + i * 8192, R, C); const int Rb = Epi::PERM ? ((R & ~31) + perm32(R & 31)) : R;
;         voffA[i] = (unsigned)(R * K + C) * 2u; voffB[i] = (unsigned)(Rb * K + C) * 2u; }
;     const size_t kstep = (size_t)(BK * 2);
;     const size_t hstep = (size_t)HALF * K * 2;
;     const size_t tstep = 2 * hstep;
;     const unsigned ldsw = (unsigned)wid * 1024u;
;     const int aoff = lds_byte(wr * 64 + fr, fq * 8), boff = lds_byte(wc * 32 + fr, fq * 8);
;     ...
;     if constexpr (SP2) {
;         PG8_STAGE(PG8_SB(0, 0), cB, voffB); PG8_STAGE(PG8_SB(0, 1), cB + hstep, voffB); PG8_STAGE(PG8_SA(0, 0), cA, voffA); PG8_STAGE(PG8_SA(0, 1), cA + hstep, voffA);
;         if (wr == 1) PG8_BAR;
;         PG8_WAIT_V(2); PG8_BAR;
;         PG8_STAGE(PG8_SB(1, 0), cB + kstep, voffB); PG8_STAGE(PG8_SA(1, 0), cA + kstep, voffA); PG8_STAGE(PG8_SB(1, 1), cB + hstep + kstep, voffB);
;         PG8_WAIT_V(6); PG8_BAR;
.LBB0_202:
	v_readlane_b32 s8, v254, 55
	v_readlane_b32 s9, v254, 56
	s_lshl_b64 s[8:9], s[8:9], 15
	v_readlane_b32 s3, v252, 31
	s_add_u32 s27, s3, s8
	v_readlane_b32 s3, v252, 32
	v_readlane_b32 s14, v253, 27
	s_addc_u32 s28, s3, s9
	s_lshl_b32 s2, s2, 5
	v_mov_b32_e32 v149, v161
	v_readlane_b32 s15, v253, 28
	s_and_b32 s10, s2, 0x60
	s_add_i32 m0, s23, 0x18000
	v_lshl_add_u64 v[0:1], v[0:1], 0, s[38:39]
	v_lshl_add_u64 v[12:13], s[14:15], 0, v[148:149]
	v_mov_b32_e32 v147, v161
	s_lshl_b32 s8, s1, 13
	s_lshl_b32 s9, s10, 7
	global_load_lds_dwordx4 v[0:1], off
	v_lshl_add_u64 v[0:1], v[2:3], 0, s[38:39]
	s_add_i32 m0, s23, 0x1a000
	s_add_i32 s29, s23, 0x8000
	s_add_i32 s30, s23, 0xa000
	v_lshl_add_u64 v[14:15], s[14:15], 0, v[146:147]
	global_load_lds_dwordx4 v[0:1], off
	v_lshl_add_u64 v[0:1], v[12:13], 0, s[38:39]
	s_mov_b32 m0, s29
	s_add_u32 s2, s18, 0x40080
	global_load_lds_dwordx4 v[0:1], off
	v_lshl_add_u64 v[0:1], v[14:15], 0, s[38:39]
	s_mov_b32 m0, s30
	s_addc_u32 s3, s19, 0
	global_load_lds_dwordx4 v[0:1], off
	s_add_i32 m0, s23, 0x1c000
	v_lshl_add_u64 v[0:1], s[2:3], 0, v[160:161]
	global_load_lds_dwordx4 v[0:1], off
	v_lshl_add_u64 v[0:1], s[2:3], 0, v[144:145]
	s_add_i32 m0, s23, 0x1e000
	s_cmpk_lt_u32 s0, 0x100
	global_load_lds_dwordx4 v[0:1], off
	s_waitcnt vmcnt(8)
	s_barrier
	v_lshrrev_b32_e32 v1, 1, v4
	v_and_b32_e32 v1, 24, v1
	v_and_b32_e32 v0, 15, v4
	v_lshlrev_b32_e32 v2, 1, v1
	v_lshl_or_b32 v167, s1, 6, v0
	v_lshl_or_b32 v0, v0, 6, v2
	v_lshlrev_b32_e32 v2, 2, v4
	v_and_b32_e32 v2, 32, v2
	v_bitop3_b32 v3, v0, s8, v2 bitop3:0xde
	v_bitop3_b32 v169, v0, s9, v2 bitop3:0xde
	v_lshlrev_b32_e32 v0, 14, v9
	v_and_b32_e32 v0, 0xffff8000, v0
	v_or_b32_e32 v170, s10, v1
	v_lshl_add_u32 v0, v8, 11, v0
	v_and_b32_e32 v1, 1, v9
	v_lshl_or_b32 v0, v1, 6, v0
	v_lshl_add_u32 v150, v10, 1, v0
	v_lshlrev_b32_e32 v0, 14, v5
	v_and_b32_e32 v0, 0xffff8000, v0
	s_waitcnt vmcnt(6)
	v_lshl_add_u32 v0, v6, 11, v0
	v_and_b32_e32 v1, 1, v5
	v_lshl_or_b32 v0, v1, 6, v0
	v_readlane_b32 s0, v253, 25
	s_cselect_b64 s[8:9], -1, 0
	v_mov_b32_e32 v151, v161
	v_lshl_add_u32 v152, v7, 1, v0
	v_mov_b32_e32 v153, v161
	s_mov_b32 s78, 0
	v_add_u32_e32 v171, 0, v3
	v_readlane_b32 s33, v253, 12
	s_mov_b32 s31, s0
	s_mov_b64 s[2:3], s[14:15]
	s_barrier
	v_readlane_b32 s1, v253, 26
	s_branch .LBB0_205

; __device__ __forceinline__ int opaque_tid() { int t = threadIdx.x; asm volatile("" : "+v"(t)); return t; }
; #define PG8_STAGE(bufoff, gbase, voff) do { _Pragma("unroll") for (int _i = 0; _i < 2; ++_i) \
;         __builtin_amdgcn_global_load_lds((const unsigned*)((const char*)(gbase) + (voff)[_i]), (PG8_LAS unsigned*)(lds + (bufoff) + ldsw + _i * 8192), 16, 0, 0); } while (0)
; #define PG8_WAIT_V(n) asm volatile("s_waitcnt vmcnt(" #n ")" ::: "memory")
; #define PG8_BAR __builtin_amdgcn_s_barrier()
; template <class Epi, class Sched, bool ALIGN_EPI = false, bool SP2 = false>
; __device__ __forceinline__ void gemm_phase(PG8_LAS unsigned char* lds, const Gemm g, const Sched& S, const Epi& E) {
;     const int tid = opaque_tid(), wid = __builtin_amdgcn_readfirstlane(tid >> 6), lane = tid & 63, wr = wid >> 2, wc = wid & 3, fr = lane & 15, fq = lane >> 4;
;     const int K = g.K, nt = K / BK;
;     unsigned voffA[2], voffB[2];
; #pragma unroll
;     for (int i = 0; i < 2; ++i) { int R, C; stage_rc(tid * 16 + i * 8192, R, C); const int Rb = Epi::PERM ? ((R & ~31) + perm32(R & 31)) : R;
;         voffA[i] = (unsigned)(R * K + C) * 2u; voffB[i] = (unsigned)(Rb * K + C) * 2u; }
;     const size_t kstep = (size_t)(BK * 2);
;     const size_t hstep = (size_t)HALF * K * 2;
;     const size_t tstep = 2 * hstep;
;     const unsigned ldsw = (unsigned)wid * 1024u;
;     const int aoff = lds_byte(wr * 64 + fr, fq * 8), boff = lds_byte(wc * 32 + fr, fq * 8);
;     ...
;     if constexpr (SP2) {
;         PG8_STAGE(PG8_SB(0, 0), cB, voffB); PG8_STAGE(PG8_SB(0, 1), cB + hstep, voffB); PG8_STAGE(PG8_SA(0, 0), cA, voffA); PG8_STAGE(PG8_SA(0, 1), cA + hstep, voffA);
;         if (wr == 1) PG8_BAR;
;         PG8_WAIT_V(2); PG8_BAR;
;         PG8_STAGE(PG8_SB(1, 0), cB + kstep, voffB); PG8_STAGE(PG8_SA(1, 0), cA + kstep, voffA); PG8_STAGE(PG8_SB(1, 1), cB + hstep + kstep, voffB);
;         PG8_WAIT_V(6); PG8_BAR;
.LBB0_358:
	v_readlane_b32 s14, v254, 63
	v_readlane_b32 s15, v255, 0
	s_lshl_b64 s[14:15], s[14:15], 2
	v_readlane_b32 s40, v254, 15
	v_readlane_b32 s41, v254, 16
	s_add_u32 s14, s40, s14
	s_addc_u32 s15, s41, s15
	s_add_i32 m0, s31, 0x18000
	v_lshl_add_u64 v[0:1], v[0:1], 0, s[38:39]
	global_load_lds_dwordx4 v[0:1], off
	v_lshl_add_u64 v[0:1], v[2:3], 0, s[38:39]
	s_add_i32 m0, s31, 0x1a000
	s_add_i32 s37, s31, 0x8000
	global_load_lds_dwordx4 v[0:1], off
	v_lshl_add_u64 v[0:1], v[8:9], 0, s[38:39]
	s_mov_b32 m0, s37
	s_add_i32 s40, s31, 0xa000
	global_load_lds_dwordx4 v[0:1], off
	v_lshl_add_u64 v[0:1], v[10:11], 0, s[38:39]
	s_mov_b32 m0, s40
	s_lshr_b32 s1, s1, 26
	global_load_lds_dwordx4 v[0:1], off
	s_add_i32 m0, s31, 0x1c000
	v_lshl_add_u64 v[0:1], v[4:5], 0, s[38:39]
	global_load_lds_dwordx4 v[0:1], off
	v_lshl_add_u64 v[0:1], v[6:7], 0, s[38:39]
	s_add_i32 m0, s31, 0x1e000
	s_add_i32 s1, s0, s1
	global_load_lds_dwordx4 v[0:1], off
	s_waitcnt vmcnt(8)
	s_barrier
	v_and_b32_e32 v0, 15, v12
	v_and_b32_e32 v1, 48, v12
	v_lshlrev_b32_e32 v0, 6, v0
	v_lshlrev_b32_e32 v3, 2, v12
	s_ashr_i32 s41, s1, 6
	v_or_b32_e32 v2, v0, v1
	s_lshl_b32 s1, s16, 13
	v_and_b32_e32 v3, 32, v3
	v_bitop3_b32 v0, v0, v3, v1 bitop3:0x36
	v_bitop3_b32 v1, v2, s1, v3 bitop3:0xde
	s_lshl_b32 s1, s3, 12
	s_and_b32 s1, s1, 0x3000
	v_readlane_b32 s42, v254, 17
	v_or_b32_e32 v141, s1, v0
	s_cmp_gt_i32 s0, 63
	v_add_u32_e32 v0, v18, v16
	s_waitcnt vmcnt(6)
	s_cselect_b64 s[16:17], -1, 0
	s_add_i32 s42, s41, -2
	v_add_lshl_u32 v160, v0, v17, 1
	v_add_u32_e32 v0, v15, v13
	v_readlane_b32 s45, v254, 20
	s_cmpk_lt_u32 s2, 0x100
	v_lshl_add_u64 v[136:137], s[8:9], 0, v[160:161]
	v_add_lshl_u32 v160, v0, v14, 1
	v_readlane_b32 s43, v254, 18
	v_readlane_b32 s44, v254, 19
	s_cselect_b64 s[18:19], -1, 0
	v_lshl_add_u64 v[138:139], s[8:9], 0, v[160:161]
	s_mov_b32 s78, 0
	v_add_u32_e32 v145, 0, v1
	v_readlane_b32 s33, v253, 13
	v_readlane_b32 s45, v253, 33
	v_readlane_b32 s46, v254, 21
	v_readlane_b32 s47, v254, 22
	s_barrier
	s_branch .LBB0_361

; __device__ __forceinline__ int opaque_tid() { int t = threadIdx.x; asm volatile("" : "+v"(t)); return t; }
; #define PG8_STAGE(bufoff, gbase, voff) do { _Pragma("unroll") for (int _i = 0; _i < 2; ++_i) \
;         __builtin_amdgcn_global_load_lds((const unsigned*)((const char*)(gbase) + (voff)[_i]), (PG8_LAS unsigned*)(lds + (bufoff) + ldsw + _i * 8192), 16, 0, 0); } while (0)
; #define PG8_WAIT_V(n) asm volatile("s_waitcnt vmcnt(" #n ")" ::: "memory")
; #define PG8_BAR __builtin_amdgcn_s_barrier()
; template <class Epi, class Sched, bool ALIGN_EPI = false, bool SP2 = false>
; __device__ __forceinline__ void gemm_phase(PG8_LAS unsigned char* lds, const Gemm g, const Sched& S, const Epi& E) {
;     const int tid = opaque_tid(), wid = __builtin_amdgcn_readfirstlane(tid >> 6), lane = tid & 63, wr = wid >> 2, wc = wid & 3, fr = lane & 15, fq = lane >> 4;
;     const int K = g.K, nt = K / BK;
;     unsigned voffA[2], voffB[2];
; #pragma unroll
;     for (int i = 0; i < 2; ++i) { int R, C; stage_rc(tid * 16 + i * 8192, R, C); const int Rb = Epi::PERM ? ((R & ~31) + perm32(R & 31)) : R;
;         voffA[i] = (unsigned)(R * K + C) * 2u; voffB[i] = (unsigned)(Rb * K + C) * 2u; }
;     const size_t kstep = (size_t)(BK * 2);
;     const size_t hstep = (size_t)HALF * K * 2;
;     const size_t tstep = 2 * hstep;
;     const unsigned ldsw = (unsigned)wid * 1024u;
;     const int aoff = lds_byte(wr * 64 + fr, fq * 8), boff = lds_byte(wc * 32 + fr, fq * 8);
;     ...
;     if constexpr (SP2) {
;         PG8_STAGE(PG8_SB(0, 0), cB, voffB); PG8_STAGE(PG8_SB(0, 1), cB + hstep, voffB); PG8_STAGE(PG8_SA(0, 0), cA, voffA); PG8_STAGE(PG8_SA(0, 1), cA + hstep, voffA);
;         if (wr == 1) PG8_BAR;
;         PG8_WAIT_V(2); PG8_BAR;
;         PG8_STAGE(PG8_SB(1, 0), cB + kstep, voffB); PG8_STAGE(PG8_SA(1, 0), cA + kstep, voffA); PG8_STAGE(PG8_SB(1, 1), cB + hstep + kstep, voffB);
;         PG8_WAIT_V(6); PG8_BAR;
.LBB0_416:
	v_readlane_b32 s40, v254, 15
	s_lshl_b64 s[6:7], s[6:7], 2
	v_readlane_b32 s44, v254, 19
	v_readlane_b32 s45, v254, 20
	s_add_u32 s6, s44, s6
	s_addc_u32 s7, s45, s7
	v_and_b32_e32 v9, 15, v8
	s_lshr_b32 s1, s1, 26
	s_add_i32 s1, s0, s1
	v_and_b32_e32 v10, 48, v8
	v_lshlrev_b32_e32 v9, 6, v9
	v_lshlrev_b32_e32 v8, 2, v8
	s_ashr_i32 s35, s1, 6
	v_or_b32_e32 v11, v9, v10
	s_lshl_b32 s1, s16, 13
	v_and_b32_e32 v8, 32, v8
	v_bitop3_b32 v9, v9, v8, v10 bitop3:0x36
	v_bitop3_b32 v10, v11, s1, v8 bitop3:0xde
	s_lshl_b32 s1, s3, 12
	s_and_b32 s1, s1, 0x3000
	v_or_b32_e32 v156, s1, v9
	v_readlane_b32 s1, v254, 53
	s_add_u32 s16, s1, 0x440080
	v_readlane_b32 s1, v254, 54
	s_addc_u32 s17, s1, 0
	s_add_i32 m0, s29, 0x18000
	v_lshl_add_u64 v[8:9], s[16:17], 0, v[140:141]
	global_load_lds_dwordx4 v[8:9], off
	v_lshl_add_u64 v[8:9], s[16:17], 0, v[136:137]
	s_add_i32 m0, s29, 0x1a000
	s_add_i32 s36, s29, 0x8000
	global_load_lds_dwordx4 v[8:9], off
	v_lshl_add_u64 v[4:5], v[4:5], 0, s[38:39]
	s_mov_b32 m0, s36
	s_add_i32 s37, s29, 0xa000
	global_load_lds_dwordx4 v[4:5], off
	v_lshl_add_u64 v[4:5], v[6:7], 0, s[38:39]
	s_mov_b32 m0, s37
	v_lshl_add_u64 v[0:1], v[0:1], 0, s[38:39]
	global_load_lds_dwordx4 v[4:5], off
	s_add_i32 m0, s29, 0x1c000
	v_readlane_b32 s41, v254, 16
	global_load_lds_dwordx4 v[0:1], off
	v_lshl_add_u64 v[0:1], v[2:3], 0, s[38:39]
	s_add_i32 m0, s29, 0x1e000
	s_cmp_gt_i32 s0, 63
	global_load_lds_dwordx4 v[0:1], off
	s_waitcnt vmcnt(8)
	s_barrier
	s_waitcnt vmcnt(6)
	s_cselect_b64 s[16:17], -1, 0
	s_add_i32 s40, s35, -2
	s_cmpk_lt_u32 s2, 0x100
	v_readlane_b32 s0, v253, 14
	s_mov_b32 s18, 0
	s_cselect_b64 s[20:21], -1, 0
	v_add_u32_e32 v157, 0, v10
	s_mov_b32 s24, s0
	v_readlane_b32 s42, v254, 17
	v_readlane_b32 s43, v254, 18
	v_readlane_b32 s46, v254, 21
	v_readlane_b32 s47, v254, 22
	s_barrier
	s_branch .LBB0_419

; __device__ __forceinline__ int opaque_tid() { int t = threadIdx.x; asm volatile("" : "+v"(t)); return t; }
; #define PG8_STAGE(bufoff, gbase, voff) do { _Pragma("unroll") for (int _i = 0; _i < 2; ++_i) \
;         __builtin_amdgcn_global_load_lds((const unsigned*)((const char*)(gbase) + (voff)[_i]), (PG8_LAS unsigned*)(lds + (bufoff) + ldsw + _i * 8192), 16, 0, 0); } while (0)
; #define PG8_WAIT_V(n) asm volatile("s_waitcnt vmcnt(" #n ")" ::: "memory")
; #define PG8_BAR __builtin_amdgcn_s_barrier()
; template <class Epi, class Sched, bool ALIGN_EPI = false, bool SP2 = false>
; __device__ __forceinline__ void gemm_phase(PG8_LAS unsigned char* lds, const Gemm g, const Sched& S, const Epi& E) {
;     const int tid = opaque_tid(), wid = __builtin_amdgcn_readfirstlane(tid >> 6), lane = tid & 63, wr = wid >> 2, wc = wid & 3, fr = lane & 15, fq = lane >> 4;
;     const int K = g.K, nt = K / BK;
;     unsigned voffA[2], voffB[2];
; #pragma unroll
;     for (int i = 0; i < 2; ++i) { int R, C; stage_rc(tid * 16 + i * 8192, R, C); const int Rb = Epi::PERM ? ((R & ~31) + perm32(R & 31)) : R;
;         voffA[i] = (unsigned)(R * K + C) * 2u; voffB[i] = (unsigned)(Rb * K + C) * 2u; }
;     const size_t kstep = (size_t)(BK * 2);
;     const size_t hstep = (size_t)HALF * K * 2;
;     const size_t tstep = 2 * hstep;
;     const unsigned ldsw = (unsigned)wid * 1024u;
;     const int aoff = lds_byte(wr * 64 + fr, fq * 8), boff = lds_byte(wc * 32 + fr, fq * 8);
;     ...
;     if constexpr (SP2) {
;         PG8_STAGE(PG8_SB(0, 0), cB, voffB); PG8_STAGE(PG8_SB(0, 1), cB + hstep, voffB); PG8_STAGE(PG8_SA(0, 0), cA, voffA); PG8_STAGE(PG8_SA(0, 1), cA + hstep, voffA);
;         if (wr == 1) PG8_BAR;
;         PG8_WAIT_V(2); PG8_BAR;
;         PG8_STAGE(PG8_SB(1, 0), cB + kstep, voffB); PG8_STAGE(PG8_SA(1, 0), cA + kstep, voffA); PG8_STAGE(PG8_SB(1, 1), cB + hstep + kstep, voffB);
;         PG8_WAIT_V(6); PG8_BAR;
.LBB0_439:
	v_readlane_b32 s12, v254, 63
	v_readlane_b32 s13, v255, 0
	v_readlane_b32 s40, v254, 15
	s_lshl_b64 s[12:13], s[12:13], 2
	v_readlane_b32 s42, v254, 17
	v_readlane_b32 s43, v254, 18
	s_add_u32 s12, s42, s12
	s_addc_u32 s13, s43, s13
	s_add_i32 m0, s29, 0x18000
	v_lshl_add_u64 v[0:1], v[0:1], 0, s[38:39]
	global_load_lds_dwordx4 v[0:1], off
	v_lshl_add_u64 v[0:1], v[2:3], 0, s[38:39]
	s_add_i32 m0, s29, 0x1a000
	s_add_i32 s35, s29, 0x8000
	global_load_lds_dwordx4 v[0:1], off
	v_lshl_add_u64 v[0:1], v[8:9], 0, s[38:39]
	s_mov_b32 m0, s35
	s_add_i32 s36, s29, 0xa000
	global_load_lds_dwordx4 v[0:1], off
	v_lshl_add_u64 v[0:1], v[10:11], 0, s[38:39]
	s_mov_b32 m0, s36
	s_lshr_b32 s1, s1, 26
	global_load_lds_dwordx4 v[0:1], off
	s_add_i32 m0, s29, 0x1c000
	v_lshl_add_u64 v[0:1], v[4:5], 0, s[38:39]
	global_load_lds_dwordx4 v[0:1], off
	v_lshl_add_u64 v[0:1], v[6:7], 0, s[38:39]
	s_add_i32 m0, s29, 0x1e000
	s_add_i32 s1, s0, s1
	global_load_lds_dwordx4 v[0:1], off
	s_waitcnt vmcnt(8)
	s_barrier
	v_and_b32_e32 v0, 15, v12
	v_and_b32_e32 v1, 48, v12
	v_lshlrev_b32_e32 v0, 6, v0
	v_lshlrev_b32_e32 v3, 2, v12
	s_ashr_i32 s37, s1, 6
	v_or_b32_e32 v2, v0, v1
	s_lshl_b32 s1, s14, 13
	v_and_b32_e32 v3, 32, v3
	v_bitop3_b32 v0, v0, v3, v1 bitop3:0x36
	v_bitop3_b32 v1, v2, s1, v3 bitop3:0xde
	s_lshl_b32 s1, s7, 12
	s_and_b32 s1, s1, 0x3000
	v_or_b32_e32 v147, s1, v0
	s_cmp_gt_i32 s0, 63
	v_add_u32_e32 v0, v18, v16
	s_waitcnt vmcnt(6)
	s_cselect_b64 s[14:15], -1, 0
	s_add_i32 s40, s37, -2
	v_add_lshl_u32 v160, v0, v17, 1
	v_add_u32_e32 v0, v15, v13
	s_cmpk_lt_u32 s6, 0x100
	v_lshl_add_u64 v[136:137], s[2:3], 0, v[160:161]
	v_add_lshl_u32 v160, v0, v14, 1
	v_readlane_b32 s0, v253, 41
	v_readlane_b32 s41, v254, 16
	s_cselect_b64 s[16:17], -1, 0
	v_lshl_add_u64 v[138:139], s[2:3], 0, v[160:161]
	s_mov_b32 s78, 0
	v_add_u32_e32 v148, 0, v1
	v_readlane_b32 s33, v253, 16
	s_mov_b32 s43, s0
	v_readlane_b32 s44, v254, 19
	v_readlane_b32 s45, v254, 20
	v_readlane_b32 s46, v254, 21
	v_readlane_b32 s47, v254, 22
	s_barrier
	v_readlane_b32 s1, v253, 42
	s_branch .LBB0_442

; __device__ __forceinline__ int opaque_tid() { int t = threadIdx.x; asm volatile("" : "+v"(t)); return t; }
; #define PG8_STAGE(bufoff, gbase, voff) do { _Pragma("unroll") for (int _i = 0; _i < 2; ++_i) \
;         __builtin_amdgcn_global_load_lds((const unsigned*)((const char*)(gbase) + (voff)[_i]), (PG8_LAS unsigned*)(lds + (bufoff) + ldsw + _i * 8192), 16, 0, 0); } while (0)
; #define PG8_WAIT_V(n) asm volatile("s_waitcnt vmcnt(" #n ")" ::: "memory")
; #define PG8_BAR __builtin_amdgcn_s_barrier()
; template <class Epi, class Sched, bool ALIGN_EPI = false, bool SP2 = false>
; __device__ __forceinline__ void gemm_phase(PG8_LAS unsigned char* lds, const Gemm g, const Sched& S, const Epi& E) {
;     const int tid = opaque_tid(), wid = __builtin_amdgcn_readfirstlane(tid >> 6), lane = tid & 63, wr = wid >> 2, wc = wid & 3, fr = lane & 15, fq = lane >> 4;
;     const int K = g.K, nt = K / BK;
;     unsigned voffA[2], voffB[2];
; #pragma unroll
;     for (int i = 0; i < 2; ++i) { int R, C; stage_rc(tid * 16 + i * 8192, R, C); const int Rb = Epi::PERM ? ((R & ~31) + perm32(R & 31)) : R;
;         voffA[i] = (unsigned)(R * K + C) * 2u; voffB[i] = (unsigned)(Rb * K + C) * 2u; }
;     const size_t kstep = (size_t)(BK * 2);
;     const size_t hstep = (size_t)HALF * K * 2;
;     const size_t tstep = 2 * hstep;
;     const unsigned ldsw = (unsigned)wid * 1024u;
;     const int aoff = lds_byte(wr * 64 + fr, fq * 8), boff = lds_byte(wc * 32 + fr, fq * 8);
;     ...
;     if constexpr (SP2) {
;         PG8_STAGE(PG8_SB(0, 0), cB, voffB); PG8_STAGE(PG8_SB(0, 1), cB + hstep, voffB); PG8_STAGE(PG8_SA(0, 0), cA, voffA); PG8_STAGE(PG8_SA(0, 1), cA + hstep, voffA);
;         if (wr == 1) PG8_BAR;
;         PG8_WAIT_V(2); PG8_BAR;
;         PG8_STAGE(PG8_SB(1, 0), cB + kstep, voffB); PG8_STAGE(PG8_SA(1, 0), cA + kstep, voffA); PG8_STAGE(PG8_SB(1, 1), cB + hstep + kstep, voffB);
;         PG8_WAIT_V(6); PG8_BAR;
.LBB0_935:
	s_add_u32 s35, s24, 0x2000
	s_addc_u32 s36, s25, 0
	v_and_b32_e32 v11, 15, v10
	s_add_u32 s37, s24, 0x4000
	v_and_b32_e32 v16, 48, v10
	v_lshlrev_b32_e32 v11, 6, v11
	v_lshlrev_b32_e32 v10, 2, v10
	s_addc_u32 s40, s25, 0
	v_or_b32_e32 v17, v11, v16
	s_lshl_b32 s4, s4, 13
	v_and_b32_e32 v10, 32, v10
	v_bitop3_b32 v11, v11, v10, v16 bitop3:0x36
	v_bitop3_b32 v10, v17, s4, v10 bitop3:0xde
	s_lshl_b32 s1, s1, 12
	v_readlane_b32 s4, v254, 3
	s_and_b32 s1, s1, 0x3000
	v_readlane_b32 s5, v254, 4
	v_readlane_b32 s12, v252, 9
	s_and_b64 s[4:5], s[4:5], exec
	v_readlane_b32 s13, v252, 10
	v_readlane_b32 s20, v253, 37
	s_mov_b64 s[4:5], s[12:13]
	v_mov_b32_e32 v153, v161
	v_readlane_b32 s21, v253, 38
	s_cselect_b32 s11, s89, s5
	s_cselect_b32 s10, s88, s4
	s_add_i32 m0, s29, 0x18000
	v_lshl_add_u64 v[0:1], v[0:1], 0, s[38:39]
	v_lshl_add_u64 v[12:13], s[20:21], 0, v[152:153]
	v_mov_b32_e32 v151, v161
	global_load_lds_dwordx4 v[0:1], off
	v_lshl_add_u64 v[0:1], v[2:3], 0, s[38:39]
	s_add_i32 m0, s29, 0x1a000
	s_add_i32 s41, s29, 0x8000
	s_add_i32 s42, s29, 0xa000
	v_lshl_add_u64 v[14:15], s[20:21], 0, v[150:151]
	global_load_lds_dwordx4 v[0:1], off
	v_lshl_add_u64 v[0:1], v[12:13], 0, s[38:39]
	s_mov_b32 m0, s41
	s_add_u32 s4, s6, 0x40080
	global_load_lds_dwordx4 v[0:1], off
	v_lshl_add_u64 v[0:1], v[14:15], 0, s[38:39]
	s_mov_b32 m0, s42
	s_addc_u32 s5, s7, 0
	global_load_lds_dwordx4 v[0:1], off
	s_add_i32 m0, s29, 0x1c000
	v_lshl_add_u64 v[0:1], s[4:5], 0, v[160:161]
	global_load_lds_dwordx4 v[0:1], off
	v_lshl_add_u64 v[0:1], s[4:5], 0, v[148:149]
	s_add_i32 m0, s29, 0x1e000
	v_or_b32_e32 v205, s1, v11
	global_load_lds_dwordx4 v[0:1], off
	s_waitcnt vmcnt(8)
	s_barrier
	v_lshlrev_b32_e32 v0, 14, v8
	v_and_b32_e32 v0, 0xffff8000, v0
	v_lshl_add_u32 v0, v7, 11, v0
	v_and_b32_e32 v1, 1, v8
	v_lshl_or_b32 v0, v1, 6, v0
	v_lshl_add_u32 v154, v9, 1, v0
	v_lshlrev_b32_e32 v0, 14, v4
	v_and_b32_e32 v0, 0xffff8000, v0
	s_waitcnt vmcnt(6)
	v_lshl_add_u32 v0, v5, 11, v0
	v_and_b32_e32 v1, 1, v4
	s_cmpk_lt_u32 s0, 0x100
	v_lshl_or_b32 v0, v1, 6, v0
	v_readlane_b32 s0, v253, 41
	v_readlane_b32 s14, v252, 11
	v_readlane_b32 s16, v252, 13
	s_cselect_b64 s[12:13], -1, 0
	v_mov_b32_e32 v155, v161
	v_lshl_add_u32 v156, v6, 1, v0
	v_mov_b32_e32 v157, v161
	s_mov_b32 s78, 0
	v_add_u32_e32 v206, 0, v10
	v_readlane_b32 s43, v253, 16
	s_mov_b32 s33, s0
	s_mov_b64 s[4:5], s[20:21]
	v_readlane_b32 s15, v252, 12
	v_readlane_b32 s17, v252, 14
	v_readlane_b32 s18, v252, 15
	v_readlane_b32 s19, v252, 16
	s_barrier
	v_readlane_b32 s1, v253, 42
	s_branch .LBB0_938

; __device__ __forceinline__ int opaque_tid() { int t = threadIdx.x; asm volatile("" : "+v"(t)); return t; }
; #define PG8_STAGE(bufoff, gbase, voff) do { _Pragma("unroll") for (int _i = 0; _i < 2; ++_i) \
;         __builtin_amdgcn_global_load_lds((const unsigned*)((const char*)(gbase) + (voff)[_i]), (PG8_LAS unsigned*)(lds + (bufoff) + ldsw + _i * 8192), 16, 0, 0); } while (0)
; #define PG8_WAIT_V(n) asm volatile("s_waitcnt vmcnt(" #n ")" ::: "memory")
; #define PG8_BAR __builtin_amdgcn_s_barrier()
; template <class Epi, class Sched, bool ALIGN_EPI = false, bool SP2 = false>
; __device__ __forceinline__ void gemm_phase(PG8_LAS unsigned char* lds, const Gemm g, const Sched& S, const Epi& E) {
;     const int tid = opaque_tid(), wid = __builtin_amdgcn_readfirstlane(tid >> 6), lane = tid & 63, wr = wid >> 2, wc = wid & 3, fr = lane & 15, fq = lane >> 4;
;     const int K = g.K, nt = K / BK;
;     unsigned voffA[2], voffB[2];
; #pragma unroll
;     for (int i = 0; i < 2; ++i) { int R, C; stage_rc(tid * 16 + i * 8192, R, C); const int Rb = Epi::PERM ? ((R & ~31) + perm32(R & 31)) : R;
;         voffA[i] = (unsigned)(R * K + C) * 2u; voffB[i] = (unsigned)(Rb * K + C) * 2u; }
;     const size_t kstep = (size_t)(BK * 2);
;     const size_t hstep = (size_t)HALF * K * 2;
;     const size_t tstep = 2 * hstep;
;     const unsigned ldsw = (unsigned)wid * 1024u;
;     const int aoff = lds_byte(wr * 64 + fr, fq * 8), boff = lds_byte(wc * 32 + fr, fq * 8);
;     ...
;     if constexpr (SP2) {
;         PG8_STAGE(PG8_SB(0, 0), cB, voffB); PG8_STAGE(PG8_SB(0, 1), cB + hstep, voffB); PG8_STAGE(PG8_SA(0, 0), cA, voffA); PG8_STAGE(PG8_SA(0, 1), cA + hstep, voffA);
;         if (wr == 1) PG8_BAR;
;         PG8_WAIT_V(2); PG8_BAR;
;         PG8_STAGE(PG8_SB(1, 0), cB + kstep, voffB); PG8_STAGE(PG8_SA(1, 0), cA + kstep, voffA); PG8_STAGE(PG8_SB(1, 1), cB + hstep + kstep, voffB);
;         PG8_WAIT_V(6); PG8_BAR;
.LBB0_1125:
	v_readlane_b32 s6, v254, 55
	v_readlane_b32 s7, v254, 56
	s_lshl_b64 s[6:7], s[6:7], 16
	v_readlane_b32 s5, v252, 17
	v_lshrrev_b32_e32 v16, 1, v10
	s_add_u32 s31, s5, s6
	v_readlane_b32 s5, v252, 18
	v_and_b32_e32 v16, 24, v16
	v_readlane_b32 s14, v253, 19
	s_addc_u32 s34, s5, s7
	v_and_b32_e32 v11, 15, v10
	v_lshlrev_b32_e32 v17, 1, v16
	v_lshlrev_b32_e32 v10, 2, v10
	s_lshl_b32 s1, s1, 5
	v_mov_b32_e32 v149, v161
	v_readlane_b32 s15, v253, 20
	v_lshl_or_b32 v168, s4, 6, v11
	v_lshl_or_b32 v11, v11, 6, v17
	s_lshl_b32 s4, s4, 13
	v_and_b32_e32 v10, 32, v10
	s_and_b32 s1, s1, 0x60
	s_add_i32 m0, s27, 0x18000
	v_lshl_add_u64 v[0:1], v[0:1], 0, s[38:39]
	v_lshl_add_u64 v[12:13], s[14:15], 0, v[148:149]
	v_mov_b32_e32 v147, v161
	v_bitop3_b32 v17, v11, s4, v10 bitop3:0xde
	s_lshl_b32 s4, s1, 7
	global_load_lds_dwordx4 v[0:1], off
	v_lshl_add_u64 v[0:1], v[2:3], 0, s[38:39]
	s_add_i32 m0, s27, 0x1a000
	s_add_i32 s35, s27, 0x8000
	s_add_i32 s36, s27, 0xa000
	v_lshl_add_u64 v[14:15], s[14:15], 0, v[146:147]
	v_bitop3_b32 v169, v11, s4, v10 bitop3:0xde
	global_load_lds_dwordx4 v[0:1], off
	v_lshl_add_u64 v[0:1], v[12:13], 0, s[38:39]
	s_mov_b32 m0, s35
	s_add_u32 s4, s18, 0x40080
	global_load_lds_dwordx4 v[0:1], off
	v_lshl_add_u64 v[0:1], v[14:15], 0, s[38:39]
	s_mov_b32 m0, s36
	s_addc_u32 s5, s19, 0
	global_load_lds_dwordx4 v[0:1], off
	s_add_i32 m0, s27, 0x1c000
	v_lshl_add_u64 v[0:1], s[4:5], 0, v[160:161]
	global_load_lds_dwordx4 v[0:1], off
	v_lshl_add_u64 v[0:1], s[4:5], 0, v[144:145]
	s_add_i32 m0, s27, 0x1e000
	s_cmpk_lt_u32 s0, 0x100
	global_load_lds_dwordx4 v[0:1], off
	s_waitcnt vmcnt(8)
	s_barrier
	v_lshlrev_b32_e32 v0, 14, v8
	v_and_b32_e32 v0, 0xffff8000, v0
	v_lshl_add_u32 v0, v7, 11, v0
	v_and_b32_e32 v1, 1, v8
	v_lshl_or_b32 v0, v1, 6, v0
	v_lshl_add_u32 v150, v9, 1, v0
	v_lshlrev_b32_e32 v0, 14, v4
	v_and_b32_e32 v0, 0xffff8000, v0
	s_waitcnt vmcnt(6)
	v_lshl_add_u32 v0, v5, 11, v0
	v_and_b32_e32 v1, 1, v4
	v_or_b32_e32 v170, s1, v16
	v_lshl_or_b32 v0, v1, 6, v0
	v_readlane_b32 s0, v253, 17
	s_cselect_b64 s[6:7], -1, 0
	v_mov_b32_e32 v151, v161
	v_lshl_add_u32 v152, v6, 1, v0
	v_mov_b32_e32 v153, v161
	s_mov_b32 s78, 0
	v_add_u32_e32 v171, 0, v17
	v_readlane_b32 s37, v253, 9
	s_mov_b32 s33, s0
	s_mov_b64 s[4:5], s[14:15]
	s_barrier
	v_readlane_b32 s1, v253, 18
	s_branch .LBB0_1128

; __device__ __forceinline__ int opaque_tid() { int t = threadIdx.x; asm volatile("" : "+v"(t)); return t; }
; #define PG8_STAGE(bufoff, gbase, voff) do { _Pragma("unroll") for (int _i = 0; _i < 2; ++_i) \
;         __builtin_amdgcn_global_load_lds((const unsigned*)((const char*)(gbase) + (voff)[_i]), (PG8_LAS unsigned*)(lds + (bufoff) + ldsw + _i * 8192), 16, 0, 0); } while (0)
; #define PG8_WAIT_V(n) asm volatile("s_waitcnt vmcnt(" #n ")" ::: "memory")
; #define PG8_BAR __builtin_amdgcn_s_barrier()
; template <class Epi, class Sched, bool ALIGN_EPI = false, bool SP2 = false>
; __device__ __forceinline__ void gemm_phase(PG8_LAS unsigned char* lds, const Gemm g, const Sched& S, const Epi& E) {
;     const int tid = opaque_tid(), wid = __builtin_amdgcn_readfirstlane(tid >> 6), lane = tid & 63, wr = wid >> 2, wc = wid & 3, fr = lane & 15, fq = lane >> 4;
;     const int K = g.K, nt = K / BK;
;     unsigned voffA[2], voffB[2];
; #pragma unroll
;     for (int i = 0; i < 2; ++i) { int R, C; stage_rc(tid * 16 + i * 8192, R, C); const int Rb = Epi::PERM ? ((R & ~31) + perm32(R & 31)) : R;
;         voffA[i] = (unsigned)(R * K + C) * 2u; voffB[i] = (unsigned)(Rb * K + C) * 2u; }
;     const size_t kstep = (size_t)(BK * 2);
;     const size_t hstep = (size_t)HALF * K * 2;
;     const size_t tstep = 2 * hstep;
;     const unsigned ldsw = (unsigned)wid * 1024u;
;     const int aoff = lds_byte(wr * 64 + fr, fq * 8), boff = lds_byte(wc * 32 + fr, fq * 8);
;     ...
;     if constexpr (SP2) {
;         PG8_STAGE(PG8_SB(0, 0), cB, voffB); PG8_STAGE(PG8_SB(0, 1), cB + hstep, voffB); PG8_STAGE(PG8_SA(0, 0), cA, voffA); PG8_STAGE(PG8_SA(0, 1), cA + hstep, voffA);
;         if (wr == 1) PG8_BAR;
;         PG8_WAIT_V(2); PG8_BAR;
;         PG8_STAGE(PG8_SB(1, 0), cB + kstep, voffB); PG8_STAGE(PG8_SA(1, 0), cA + kstep, voffA); PG8_STAGE(PG8_SB(1, 1), cB + hstep + kstep, voffB);
;         PG8_WAIT_V(6); PG8_BAR;
.LBB0_1205:
	v_readlane_b32 s8, v254, 55
	s_add_u32 s24, s24, 0x5000
	v_readlane_b32 s9, v254, 56
	s_mul_i32 s78, s8, 0x6000
	s_addc_u32 s25, s25, 0
	s_lshl_b64 s[8:9], s[78:79], 2
	v_readlane_b32 s10, v252, 7
	v_readlane_b32 s11, v252, 8
	s_add_u32 s3, s10, s8
	s_addc_u32 s8, s11, s9
	s_add_u32 s35, s3, 0x19000
	s_addc_u32 s36, s8, 0
	v_readlane_b32 s8, v254, 57
	v_readlane_b32 s18, v253, 48
	v_readlane_b32 s9, v254, 58
	s_add_u32 s8, s8, 0x40000
	v_and_b32_e32 v11, 15, v10
	v_mov_b32_e32 v153, v161
	v_readlane_b32 s19, v253, 49
	s_addc_u32 s9, s9, 0
	v_and_b32_e32 v16, 48, v10
	v_lshlrev_b32_e32 v11, 6, v11
	v_lshlrev_b32_e32 v10, 2, v10
	s_lshl_b32 s1, s1, 12
	s_add_i32 m0, s29, 0x18000
	v_lshl_add_u64 v[0:1], v[0:1], 0, s[38:39]
	v_lshl_add_u64 v[12:13], s[18:19], 0, v[152:153]
	v_mov_b32_e32 v151, v161
	v_or_b32_e32 v17, v11, v16
	s_lshl_b32 s2, s2, 13
	v_and_b32_e32 v10, 32, v10
	s_and_b32 s1, s1, 0x3000
	global_load_lds_dwordx4 v[0:1], off
	v_lshl_add_u64 v[0:1], v[2:3], 0, s[38:39]
	s_add_i32 m0, s29, 0x1a000
	s_add_i32 s37, s29, 0x8000
	s_add_i32 s40, s29, 0xa000
	v_lshl_add_u64 v[14:15], s[18:19], 0, v[150:151]
	v_bitop3_b32 v11, v11, v10, v16 bitop3:0x36
	v_bitop3_b32 v10, v17, s2, v10 bitop3:0xde
	global_load_lds_dwordx4 v[0:1], off
	v_lshl_add_u64 v[0:1], v[12:13], 0, s[38:39]
	s_mov_b32 m0, s37
	s_add_u32 s2, s4, 0x100080
	global_load_lds_dwordx4 v[0:1], off
	v_lshl_add_u64 v[0:1], v[14:15], 0, s[38:39]
	s_mov_b32 m0, s40
	s_addc_u32 s3, s5, 0
	global_load_lds_dwordx4 v[0:1], off
	s_add_i32 m0, s29, 0x1c000
	v_lshl_add_u64 v[0:1], s[2:3], 0, v[160:161]
	global_load_lds_dwordx4 v[0:1], off
	v_lshl_add_u64 v[0:1], s[2:3], 0, v[148:149]
	s_add_i32 m0, s29, 0x1e000
	v_or_b32_e32 v188, s1, v11
	global_load_lds_dwordx4 v[0:1], off
	s_waitcnt vmcnt(8)
	s_barrier
	v_lshlrev_b32_e32 v0, 16, v8
	v_and_b32_e32 v0, 0xfffe0000, v0
	v_lshl_add_u32 v0, v7, 13, v0
	v_and_b32_e32 v1, 1, v8
	v_lshl_or_b32 v0, v1, 6, v0
	v_lshl_add_u32 v154, v9, 1, v0
	v_lshlrev_b32_e32 v0, 16, v4
	s_cmpk_lt_u32 s0, 0x100
	v_readlane_b32 s0, v254, 3
	v_and_b32_e32 v0, 0xfffe0000, v0
	s_waitcnt vmcnt(6)
	v_readlane_b32 s1, v254, 4
	v_lshl_add_u32 v0, v5, 13, v0
	v_and_b32_e32 v1, 1, v4
	s_cselect_b64 s[10:11], -1, 0
	s_nor_b64 s[12:13], s[0:1], s[80:81]
	v_lshl_or_b32 v0, v1, 6, v0
	v_readlane_b32 s0, v253, 41
	v_mov_b32_e32 v155, v161
	v_lshl_add_u32 v156, v6, 1, v0
	v_mov_b32_e32 v157, v161
	s_mov_b32 s78, 0
	v_add_u32_e32 v189, 0, v10
	v_readlane_b32 s41, v253, 16
	s_mov_b32 s33, s0
	s_mov_b64 s[2:3], s[18:19]
	s_barrier
	v_readlane_b32 s1, v253, 42
	s_branch .LBB0_1208
